# input-GEMM K-loop head restored to its 8-byte phase (one 4-byte pad in the phase prologue; earlier edits had shifted it by 4 bytes)
# speedup vs baseline: 1.0053x; 1.0006x over previous
.LBB0_774:
	v_readlane_b32 s6, v252, 9
	v_readlane_b32 s1, v251, 25
	v_readlane_b32 s7, v252, 10
	s_mov_b64 s[8:9], 0x80
	s_mov_b32 m0, s1
	s_and_b32 s1, s7, 0x60
	v_lshl_add_u64 v[6:7], v[6:7], 0, s[8:9]
	v_readlane_b32 s6, v251, 26
	s_lshr_b32 s5, s1, 3
	s_waitcnt vmcnt(2)
	s_barrier
	global_load_lds_dwordx4 v[6:7], off
	v_lshl_add_u64 v[4:5], v[4:5], 0, s[8:9]
	s_mov_b32 m0, s6
	v_lshl_add_u64 v[0:1], v[0:1], 0, s[8:9]
	global_load_lds_dwordx4 v[4:5], off
	s_mov_b32 m0, s92
	s_add_u32 s6, s28, 0x40080
	global_load_lds_dwordx4 v[0:1], off
	v_lshl_add_u64 v[0:1], v[2:3], 0, s[8:9]
	s_mov_b32 m0, s78
	s_addc_u32 s7, s29, 0
	v_readlane_b32 s8, v251, 28
	global_load_lds_dwordx4 v[0:1], off
	v_lshl_add_u64 v[0:1], s[6:7], 0, v[64:65]
	s_mov_b32 m0, s8
	v_ashrrev_i32_e32 v2, 6, v8
	global_load_lds_dwordx4 v[0:1], off
	v_lshl_add_u64 v[0:1], s[6:7], 0, v[154:155]
	s_add_i32 m0, s25, 0x1e000
	v_and_b32_e32 v3, 48, v8
	global_load_lds_dwordx4 v[0:1], off
	v_and_b32_e32 v0, 15, v8
	v_lshl_or_b32 v179, s4, 6, v0
	v_lshlrev_b32_e32 v4, 10, v2
	v_lshl_or_b32 v0, v0, 6, v3
	v_lshlrev_b32_e32 v3, 2, v8
	v_lshl_add_u32 v4, s4, 13, v4
	v_and_b32_e32 v3, 32, v3
	v_add_lshl_u32 v2, s5, v2, 10
	v_ashrrev_i32_e32 v1, 1, v8
	v_bitop3_b32 v4, v0, v4, v3 bitop3:0xde
	v_bitop3_b32 v181, v2, v0, v3 bitop3:0xf6
	v_lshlrev_b32_e32 v0, 14, v9
	v_and_b32_e32 v1, -8, v1
	v_and_b32_e32 v0, 0xffff8000, v0
	v_add_u32_e32 v183, s1, v1
	v_lshl_add_u32 v0, v10, 11, v0
	v_and_b32_e32 v1, 1, v9
	v_lshl_or_b32 v0, v1, 6, v0
	v_lshl_add_u32 v156, v11, 1, v0
	v_lshlrev_b32_e32 v0, 14, v12
	v_and_b32_e32 v0, 0xffff8000, v0
	s_waitcnt vmcnt(6)
	v_readlane_b32 s4, v254, 49
	v_lshl_add_u32 v0, v13, 11, v0
	v_and_b32_e32 v1, 1, v12
	s_cmp_lt_u32 s4, 4
	v_lshl_or_b32 v0, v1, 6, v0
	s_cselect_b64 s[18:19], -1, 0
	v_mov_b32_e32 v157, v65
	v_lshl_add_u32 v158, v14, 1, v0
	v_mov_b32_e32 v159, v65
	s_mov_b32 s57, 0
	v_add_u32_e32 v184, 0, v4
	s_mov_b32 s34, 0
	v_readlane_b32 s24, v254, 41
	v_readlane_b32 s27, v254, 59
	s_barrier
	s_nop 0
	s_branch .LBB0_777
